# group barriers (32 workgroups with the same blockIdx&7) for the five row-partitioned seams; placement checked by per-group XCC masks published in an earlier grid barrier, fallback to the grid barrier
# speedup vs baseline: 1.0168x; 1.0168x over previous
.LBB0_1949:
	s_cmp_gt_i32 s87, 4
	s_cselect_b64 s[0:1], -1, 0
	s_and_b64 s[2:3], s[24:25], s[0:1]
	s_andn2_b64 vcc, exec, s[2:3]
	s_cbranch_vccnz .LBB0_2003
	s_waitcnt vmcnt(0)
	s_waitcnt vmcnt(0)
	s_barrier
	s_mov_b64 s[2:3], exec
	v_readlane_b32 s4, v251, 1
	v_readlane_b32 s5, v251, 2
	s_and_b64 s[4:5], s[2:3], s[4:5]
	s_mov_b64 exec, s[4:5]
	s_cbranch_execz .LBB0_2002
	s_and_b32 s4, s90, 7
	s_lshl_b32 s4, s4, 2
	s_add_i32 s4, s4, 0x3e40
	s_lshl_b32 s5, 1, s84
	v_mov_b32_e32 v0, s4
	v_mov_b32_e32 v2, s5
	global_atomic_or v0, v2, s[96:97]
	s_waitcnt vmcnt(0)
	s_add_i32 s4, 0, 0x23fc0
	v_mov_b32_e32 v0, s4
	s_waitcnt vmcnt(0) expcnt(0) lgkmcnt(0)
	buffer_inv sc1
	ds_read_b32 v2, v0
	s_add_i32 s4, 0, 0x23fc4
	v_mov_b32_e32 v0, s4
	ds_read_b32 v0, v0
	s_waitcnt lgkmcnt(1)
	v_cmp_ne_u32_e32 vcc, 0, v2
	s_cbranch_vccnz .LBB0_1966
	v_readlane_b32 s4, v251, 0
	s_mul_i32 s18, s93, s4
	s_add_u32 s4, s96, 0x1000
	s_addc_u32 s5, s97, 0
	s_add_u32 s6, s96, 0x1100
	s_addc_u32 s7, s97, 0
	s_add_u32 s8, s96, 0x1200
	s_addc_u32 s9, s97, 0
	s_add_u32 s10, s96, 0x1300
	s_mul_i32 s18, s18, s92
	s_addc_u32 s11, s97, 0
	s_mov_b32 s19, 1
	v_mov_b32_e32 v16, 0
	s_branch .LBB0_1954

.LBB0_2170:
	s_cmp_lt_i32 s87, 6
	s_cselect_b64 s[0:1], -1, 0
	s_xor_b64 s[2:3], s[66:67], -1
	s_or_b64 s[0:1], s[2:3], s[0:1]
	s_and_b64 vcc, exec, s[0:1]
	s_cbranch_vccnz .LBB0_2224
	s_waitcnt vmcnt(0)
	s_waitcnt vmcnt(0)
	s_barrier
	s_mov_b64 s[0:1], exec
	v_readlane_b32 s2, v251, 1
	v_readlane_b32 s3, v251, 2
	s_and_b64 s[2:3], s[0:1], s[2:3]
	s_mov_b64 exec, s[2:3]
	s_cbranch_execz .LBB0_2223
	s_and_b32 s2, s90, 7
	s_lshl_b32 s2, s2, 2
	s_add_i32 s2, s2, 0x3e40
	v_mov_b32_e32 v0, s2
	global_load_dword v0, v0, s[96:97] sc1
	s_waitcnt vmcnt(0)
	v_readfirstlane_b32 s2, v0
	s_bcnt1_i32_b32 s2, s2
	s_cmp_lg_u32 s2, 1
	s_cselect_b32 s2, 1, 0
	s_cmp_lg_u32 s92, 0x100
	s_cselect_b32 s3, 1, 0
	s_or_b32 s2, s2, s3
	s_cmp_eq_u32 s2, 0
	s_cbranch_scc1 .Lplc_ok
	v_mov_b32_e32 v0, 0x3e00
	v_mov_b32_e32 v2, 1
	global_atomic_add v0, v2, s[96:97]
	s_waitcnt vmcnt(0)
